# as v12 plus the waves 4-7 row-sum adds also written as scalar v_add_f32
# baseline (speedup 1.0000x reference)
; template <int MODE> __device__ __forceinline__ void attn_unit(const Unit& a, char* shm) {
;     ...
;             f32x2 s2a = (f32x2){p0[0], p0[1]}, s2b = (f32x2){p1[0], p1[1]};
; #pragma unroll
;             for (int k2 = 1; k2 < 8; ++k2) { s2a += (f32x2){p0[2 * k2], p0[2 * k2 + 1]}; s2b += (f32x2){p1[2 * k2], p1[2 * k2 + 1]}; }
;             s2a += s2b;
;             l_reg += s2a.x + s2a.y;
.LBB0_1922:
	v_add_f32_e32 v74, v128, v140
	v_add_f32_e32 v75, v129, v141
	v_add_f32_e32 v76, v122, v138
	v_add_f32_e32 v77, v123, v139
	v_add_f32_e32 v74, v136, v74
	v_add_f32_e32 v75, v137, v75
	v_add_f32_e32 v76, v126, v76
	v_add_f32_e32 v77, v127, v77
	v_add_f32_e32 v74, v124, v74
	v_add_f32_e32 v75, v125, v75
	v_add_f32_e32 v76, v120, v76
	v_add_f32_e32 v77, v121, v77
	v_add_f32_e32 v74, v118, v74
	v_add_f32_e32 v75, v119, v75
	v_add_f32_e32 v76, v116, v76
	v_add_f32_e32 v77, v117, v77
	v_add_f32_e32 v74, v114, v74
	v_add_f32_e32 v75, v115, v75
	v_add_f32_e32 v72, v72, v76
	v_add_f32_e32 v73, v73, v77
	v_add_f32_e32 v70, v70, v74
	v_add_f32_e32 v71, v71, v75
	v_add_f32_e32 v68, v68, v72
	v_add_f32_e32 v69, v69, v73
	v_add_f32_e32 v66, v66, v70
	v_add_f32_e32 v67, v67, v71
	v_add_f32_e32 v64, v64, v68
	v_add_f32_e32 v65, v65, v69
	v_add_f32_e32 v64, v64, v66
	v_add_f32_e32 v65, v65, v67
	v_add_f32_e32 v64, v64, v65
	v_add_f32_e32 v64, v113, v64
